# EpiConv: packed f32 ops for centre tap and silu (v_pk_fma/mul/add), on top of previous stack
# speedup vs baseline: 1.0055x; 1.0019x over previous
.LBB0_1187:
	v_readlane_b32 s12, v253, 21
	v_readlane_b32 s13, v253, 22
	v_readlane_b32 s18, v253, 27
	v_readlane_b32 s19, v253, 28
	v_readlane_b32 s20, v253, 29
	v_readlane_b32 s21, v253, 30
	v_readlane_b32 s22, v253, 31
	v_readlane_b32 s23, v253, 32
	v_readlane_b32 s24, v253, 33
	v_readlane_b32 s25, v253, 34
	v_readlane_b32 s26, v253, 35
	v_readlane_b32 s27, v253, 36
	s_mov_b64 s[14:15], s[2:3]
	s_mov_b64 s[16:17], s[34:35]
	v_lshl_or_b32 v176, s66, 7, v220
	v_lshlrev_b32_e32 v208, 2, v176
	s_lshl_b32 s34, s64, 8
	s_add_i32 s34, s34, s67
	s_lshr_b32 s35, s34, 4
	v_add_u32_e32 v209, s35, v217
	v_mul_u32_u24_e32 v209, 0x5800, v209
	v_add_u32_e32 v209, v209, v208
	v_or_b32_e32 v210, s34, v217
	v_mul_u32_u24_e32 v210, 0x1600, v210
	v_lshl_add_u32 v210, v176, 1, v210
	global_load_dwordx4 v[112:115], v208, s[24:25]
	global_load_dwordx4 v[116:119], v208, s[16:17]
	global_load_dwordx4 v[120:123], v208, s[30:31]
	global_load_dwordx4 v[124:127], v208, s[26:27]
	global_load_dwordx4 v[132:135], v208, s[14:15]
	global_load_dwordx4 v[136:139], v208, s[28:29]
	global_load_dwordx4 v[140:143], v208, s[40:41]
	global_load_dwordx4 v[144:147], v208, s[44:45]
	global_load_dwordx4 v[176:179], v208, s[24:25] offset:16
	global_load_dwordx4 v[180:183], v208, s[16:17] offset:16
	global_load_dwordx4 v[184:187], v208, s[30:31] offset:16
	global_load_dwordx4 v[188:191], v208, s[26:27] offset:16
	global_load_dwordx4 v[192:195], v208, s[14:15] offset:16
	global_load_dwordx4 v[196:199], v208, s[28:29] offset:16
	global_load_dwordx4 v[200:203], v208, s[40:41] offset:16
	global_load_dwordx4 v[204:207], v208, s[44:45] offset:16
	s_and_saveexec_b64 s[2:3], s[6:7]
	global_store_dwordx4 v209, v[156:159], s[38:39]
	global_store_dwordx4 v209, v[60:63], s[38:39] offset:16
	v_add_u32_e32 v211, 0x2c00, v209
	global_store_dwordx4 v211, v[152:155], s[38:39]
	global_store_dwordx4 v211, v[56:59], s[38:39] offset:16
	v_add_u32_e32 v211, 0x2c000, v209
	global_store_dwordx4 v211, v[92:95], s[38:39]
	global_store_dwordx4 v211, v[28:31], s[38:39] offset:16
	v_add_u32_e32 v211, 0x2ec00, v209
	global_store_dwordx4 v211, v[88:91], s[38:39]
	global_store_dwordx4 v211, v[24:27], s[38:39] offset:16
	s_or_b64 exec, exec, s[2:3]
	v_add_u32_e32 v212, 0xfffbe000, v209
	s_and_saveexec_b64 s[2:3], s[8:9]
	global_store_dwordx4 v212, v[100:103], s[38:39]
	global_store_dwordx4 v212, v[36:39], s[38:39] offset:16
	v_add_u32_e32 v211, 0x2c00, v212
	global_store_dwordx4 v211, v[96:99], s[38:39]
	global_store_dwordx4 v211, v[32:35], s[38:39] offset:16
	v_add_u32_e32 v211, 0x2c000, v212
	global_store_dwordx4 v211, v[68:71], s[38:39]
	global_store_dwordx4 v211, v[4:7], s[38:39] offset:16
	v_add_u32_e32 v211, 0x2ec00, v212
	global_store_dwordx4 v211, v[64:67], s[38:39]
	global_store_dwordx4 v211, v[0:3], s[38:39] offset:16
	s_or_b64 exec, exec, s[2:3]
	v_mov_b32_e32 v238, 0xbfb8aa3b
	v_mov_b32_e32 v239, 0xbfb8aa3b
	s_waitcnt vmcnt(16)
	v_pk_fma_f32 v[224:225], v[116:117], v[156:157], v[124:125]
	v_pk_fma_f32 v[226:227], v[118:119], v[158:159], v[126:127]
	v_fmac_f32_dpp v224, v156, v112 row_shr:1 row_mask:0xf bank_mask:0xf
	v_fmac_f32_dpp v225, v157, v113 row_shr:1 row_mask:0xf bank_mask:0xf
	v_fmac_f32_dpp v226, v158, v114 row_shr:1 row_mask:0xf bank_mask:0xf
	v_fmac_f32_dpp v227, v159, v115 row_shr:1 row_mask:0xf bank_mask:0xf
	v_fmac_f32_dpp v224, v156, v120 row_shl:1 row_mask:0xf bank_mask:0xf
	v_fmac_f32_dpp v225, v157, v121 row_shl:1 row_mask:0xf bank_mask:0xf
	v_fmac_f32_dpp v226, v158, v122 row_shl:1 row_mask:0xf bank_mask:0xf
	v_fmac_f32_dpp v227, v159, v123 row_shl:1 row_mask:0xf bank_mask:0xf
	v_fmac_f32_dpp v224, v148, v120 row_shr:15 row_mask:0xf bank_mask:0xf
	v_fmac_f32_dpp v225, v149, v121 row_shr:15 row_mask:0xf bank_mask:0xf
	v_fmac_f32_dpp v226, v150, v122 row_shr:15 row_mask:0xf bank_mask:0xf
	v_fmac_f32_dpp v227, v151, v123 row_shr:15 row_mask:0xf bank_mask:0xf
	v_pk_fma_f32 v[228:229], v[136:137], v[152:153], v[144:145]
	v_pk_fma_f32 v[230:231], v[138:139], v[154:155], v[146:147]
	v_fmac_f32_dpp v228, v152, v132 row_shr:1 row_mask:0xf bank_mask:0xf
	v_fmac_f32_dpp v229, v153, v133 row_shr:1 row_mask:0xf bank_mask:0xf
	v_fmac_f32_dpp v230, v154, v134 row_shr:1 row_mask:0xf bank_mask:0xf
	v_fmac_f32_dpp v231, v155, v135 row_shr:1 row_mask:0xf bank_mask:0xf
	v_fmac_f32_dpp v228, v152, v140 row_shl:1 row_mask:0xf bank_mask:0xf
	v_fmac_f32_dpp v229, v153, v141 row_shl:1 row_mask:0xf bank_mask:0xf
	v_fmac_f32_dpp v230, v154, v142 row_shl:1 row_mask:0xf bank_mask:0xf
	v_fmac_f32_dpp v231, v155, v143 row_shl:1 row_mask:0xf bank_mask:0xf
	v_fmac_f32_dpp v228, v128, v140 row_shr:15 row_mask:0xf bank_mask:0xf
	v_fmac_f32_dpp v229, v129, v141 row_shr:15 row_mask:0xf bank_mask:0xf
	v_fmac_f32_dpp v230, v130, v142 row_shr:15 row_mask:0xf bank_mask:0xf
	v_fmac_f32_dpp v231, v131, v143 row_shr:15 row_mask:0xf bank_mask:0xf
	v_pk_mul_f32 v[232:233], v[224:225], v[238:239]
	v_pk_mul_f32 v[234:235], v[226:227], v[238:239]
	v_exp_f32_e32 v232, v232
	v_exp_f32_e32 v233, v233
	v_exp_f32_e32 v234, v234
	v_exp_f32_e32 v235, v235
	v_pk_add_f32 v[232:233], v[232:233], 1.0 op_sel_hi:[1,0]
	v_pk_add_f32 v[234:235], v[234:235], 1.0 op_sel_hi:[1,0]
	v_rcp_f32_e32 v232, v232
	v_rcp_f32_e32 v233, v233
	v_rcp_f32_e32 v234, v234
	v_rcp_f32_e32 v235, v235
	v_pk_mul_f32 v[224:225], v[224:225], v[232:233]
	v_pk_mul_f32 v[226:227], v[226:227], v[234:235]
	v_pk_mul_f32 v[224:225], v[224:225], v[228:229]
	v_pk_mul_f32 v[226:227], v[226:227], v[230:231]
	v_cvt_pk_bf16_f32 v236, v224, v225
	v_cvt_pk_bf16_f32 v237, v226, v227
	global_store_dwordx2 v210, v[236:237], s[36:37]
	v_pk_fma_f32 v[224:225], v[116:117], v[148:149], v[124:125]
	v_pk_fma_f32 v[226:227], v[118:119], v[150:151], v[126:127]
	v_fmac_f32_dpp v224, v148, v112 row_shr:1 row_mask:0xf bank_mask:0xf
	v_fmac_f32_dpp v225, v149, v113 row_shr:1 row_mask:0xf bank_mask:0xf
	v_fmac_f32_dpp v226, v150, v114 row_shr:1 row_mask:0xf bank_mask:0xf
	v_fmac_f32_dpp v227, v151, v115 row_shr:1 row_mask:0xf bank_mask:0xf
	v_fmac_f32_dpp v224, v156, v112 row_shl:15 row_mask:0xf bank_mask:0xf
	v_fmac_f32_dpp v225, v157, v113 row_shl:15 row_mask:0xf bank_mask:0xf
	v_fmac_f32_dpp v226, v158, v114 row_shl:15 row_mask:0xf bank_mask:0xf
	v_fmac_f32_dpp v227, v159, v115 row_shl:15 row_mask:0xf bank_mask:0xf
	v_fmac_f32_dpp v224, v148, v120 row_shl:1 row_mask:0xf bank_mask:0xf
	v_fmac_f32_dpp v225, v149, v121 row_shl:1 row_mask:0xf bank_mask:0xf
	v_fmac_f32_dpp v226, v150, v122 row_shl:1 row_mask:0xf bank_mask:0xf
	v_fmac_f32_dpp v227, v151, v123 row_shl:1 row_mask:0xf bank_mask:0xf
	v_fmac_f32_dpp v224, v108, v120 row_shr:15 row_mask:0xf bank_mask:0xf
	v_fmac_f32_dpp v225, v109, v121 row_shr:15 row_mask:0xf bank_mask:0xf
	v_fmac_f32_dpp v226, v110, v122 row_shr:15 row_mask:0xf bank_mask:0xf
	v_fmac_f32_dpp v227, v111, v123 row_shr:15 row_mask:0xf bank_mask:0xf
	v_pk_fma_f32 v[228:229], v[136:137], v[128:129], v[144:145]
	v_pk_fma_f32 v[230:231], v[138:139], v[130:131], v[146:147]
	v_fmac_f32_dpp v228, v128, v132 row_shr:1 row_mask:0xf bank_mask:0xf
	v_fmac_f32_dpp v229, v129, v133 row_shr:1 row_mask:0xf bank_mask:0xf
	v_fmac_f32_dpp v230, v130, v134 row_shr:1 row_mask:0xf bank_mask:0xf
	v_fmac_f32_dpp v231, v131, v135 row_shr:1 row_mask:0xf bank_mask:0xf
	v_fmac_f32_dpp v228, v152, v132 row_shl:15 row_mask:0xf bank_mask:0xf
	v_fmac_f32_dpp v229, v153, v133 row_shl:15 row_mask:0xf bank_mask:0xf
	v_fmac_f32_dpp v230, v154, v134 row_shl:15 row_mask:0xf bank_mask:0xf
	v_fmac_f32_dpp v231, v155, v135 row_shl:15 row_mask:0xf bank_mask:0xf
	v_fmac_f32_dpp v228, v128, v140 row_shl:1 row_mask:0xf bank_mask:0xf
	v_fmac_f32_dpp v229, v129, v141 row_shl:1 row_mask:0xf bank_mask:0xf
	v_fmac_f32_dpp v230, v130, v142 row_shl:1 row_mask:0xf bank_mask:0xf
	v_fmac_f32_dpp v231, v131, v143 row_shl:1 row_mask:0xf bank_mask:0xf
	v_fmac_f32_dpp v228, v104, v140 row_shr:15 row_mask:0xf bank_mask:0xf
	v_fmac_f32_dpp v229, v105, v141 row_shr:15 row_mask:0xf bank_mask:0xf
	v_fmac_f32_dpp v230, v106, v142 row_shr:15 row_mask:0xf bank_mask:0xf
	v_fmac_f32_dpp v231, v107, v143 row_shr:15 row_mask:0xf bank_mask:0xf
	v_pk_mul_f32 v[232:233], v[224:225], v[238:239]
	v_pk_mul_f32 v[234:235], v[226:227], v[238:239]
	v_exp_f32_e32 v232, v232
	v_exp_f32_e32 v233, v233
	v_exp_f32_e32 v234, v234
	v_exp_f32_e32 v235, v235
	v_pk_add_f32 v[232:233], v[232:233], 1.0 op_sel_hi:[1,0]
	v_pk_add_f32 v[234:235], v[234:235], 1.0 op_sel_hi:[1,0]
	v_rcp_f32_e32 v232, v232
	v_rcp_f32_e32 v233, v233
	v_rcp_f32_e32 v234, v234
	v_rcp_f32_e32 v235, v235
	v_pk_mul_f32 v[224:225], v[224:225], v[232:233]
	v_pk_mul_f32 v[226:227], v[226:227], v[234:235]
	v_pk_mul_f32 v[224:225], v[224:225], v[228:229]
	v_pk_mul_f32 v[226:227], v[226:227], v[230:231]
	v_cvt_pk_bf16_f32 v236, v224, v225
	v_cvt_pk_bf16_f32 v237, v226, v227
	v_add_u32_e32 v213, 0x16000, v210
	global_store_dwordx2 v213, v[236:237], s[36:37]
	v_pk_fma_f32 v[224:225], v[116:117], v[108:109], v[124:125]
	v_pk_fma_f32 v[226:227], v[118:119], v[110:111], v[126:127]
	v_fmac_f32_dpp v224, v108, v112 row_shr:1 row_mask:0xf bank_mask:0xf
	v_fmac_f32_dpp v225, v109, v113 row_shr:1 row_mask:0xf bank_mask:0xf
	v_fmac_f32_dpp v226, v110, v114 row_shr:1 row_mask:0xf bank_mask:0xf
	v_fmac_f32_dpp v227, v111, v115 row_shr:1 row_mask:0xf bank_mask:0xf
	v_fmac_f32_dpp v224, v148, v112 row_shl:15 row_mask:0xf bank_mask:0xf
	v_fmac_f32_dpp v225, v149, v113 row_shl:15 row_mask:0xf bank_mask:0xf
	v_fmac_f32_dpp v226, v150, v114 row_shl:15 row_mask:0xf bank_mask:0xf
	v_fmac_f32_dpp v227, v151, v115 row_shl:15 row_mask:0xf bank_mask:0xf
	v_fmac_f32_dpp v224, v108, v120 row_shl:1 row_mask:0xf bank_mask:0xf
	v_fmac_f32_dpp v225, v109, v121 row_shl:1 row_mask:0xf bank_mask:0xf
	v_fmac_f32_dpp v226, v110, v122 row_shl:1 row_mask:0xf bank_mask:0xf
	v_fmac_f32_dpp v227, v111, v123 row_shl:1 row_mask:0xf bank_mask:0xf
	v_fmac_f32_dpp v224, v100, v120 row_shr:15 row_mask:0xf bank_mask:0xf
	v_fmac_f32_dpp v225, v101, v121 row_shr:15 row_mask:0xf bank_mask:0xf
	v_fmac_f32_dpp v226, v102, v122 row_shr:15 row_mask:0xf bank_mask:0xf
	v_fmac_f32_dpp v227, v103, v123 row_shr:15 row_mask:0xf bank_mask:0xf
	v_pk_fma_f32 v[228:229], v[136:137], v[104:105], v[144:145]
	v_pk_fma_f32 v[230:231], v[138:139], v[106:107], v[146:147]
	v_fmac_f32_dpp v228, v104, v132 row_shr:1 row_mask:0xf bank_mask:0xf
	v_fmac_f32_dpp v229, v105, v133 row_shr:1 row_mask:0xf bank_mask:0xf
	v_fmac_f32_dpp v230, v106, v134 row_shr:1 row_mask:0xf bank_mask:0xf
	v_fmac_f32_dpp v231, v107, v135 row_shr:1 row_mask:0xf bank_mask:0xf
	v_fmac_f32_dpp v228, v128, v132 row_shl:15 row_mask:0xf bank_mask:0xf
	v_fmac_f32_dpp v229, v129, v133 row_shl:15 row_mask:0xf bank_mask:0xf
	v_fmac_f32_dpp v230, v130, v134 row_shl:15 row_mask:0xf bank_mask:0xf
	v_fmac_f32_dpp v231, v131, v135 row_shl:15 row_mask:0xf bank_mask:0xf
	v_fmac_f32_dpp v228, v104, v140 row_shl:1 row_mask:0xf bank_mask:0xf
	v_fmac_f32_dpp v229, v105, v141 row_shl:1 row_mask:0xf bank_mask:0xf
	v_fmac_f32_dpp v230, v106, v142 row_shl:1 row_mask:0xf bank_mask:0xf
	v_fmac_f32_dpp v231, v107, v143 row_shl:1 row_mask:0xf bank_mask:0xf
	v_fmac_f32_dpp v228, v96, v140 row_shr:15 row_mask:0xf bank_mask:0xf
	v_fmac_f32_dpp v229, v97, v141 row_shr:15 row_mask:0xf bank_mask:0xf
	v_fmac_f32_dpp v230, v98, v142 row_shr:15 row_mask:0xf bank_mask:0xf
	v_fmac_f32_dpp v231, v99, v143 row_shr:15 row_mask:0xf bank_mask:0xf
	v_pk_mul_f32 v[232:233], v[224:225], v[238:239]
	v_pk_mul_f32 v[234:235], v[226:227], v[238:239]
	v_exp_f32_e32 v232, v232
	v_exp_f32_e32 v233, v233
	v_exp_f32_e32 v234, v234
	v_exp_f32_e32 v235, v235
	v_pk_add_f32 v[232:233], v[232:233], 1.0 op_sel_hi:[1,0]
	v_pk_add_f32 v[234:235], v[234:235], 1.0 op_sel_hi:[1,0]
	v_rcp_f32_e32 v232, v232
	v_rcp_f32_e32 v233, v233
	v_rcp_f32_e32 v234, v234
	v_rcp_f32_e32 v235, v235
	v_pk_mul_f32 v[224:225], v[224:225], v[232:233]
	v_pk_mul_f32 v[226:227], v[226:227], v[234:235]
	v_pk_mul_f32 v[224:225], v[224:225], v[228:229]
	v_pk_mul_f32 v[226:227], v[226:227], v[230:231]
	v_cvt_pk_bf16_f32 v236, v224, v225
	v_cvt_pk_bf16_f32 v237, v226, v227
	v_add_u32_e32 v213, 0x2c000, v210
	global_store_dwordx2 v213, v[236:237], s[36:37]
	v_pk_fma_f32 v[224:225], v[116:117], v[100:101], v[124:125]
	v_pk_fma_f32 v[226:227], v[118:119], v[102:103], v[126:127]
	v_fmac_f32_dpp v224, v100, v112 row_shr:1 row_mask:0xf bank_mask:0xf
	v_fmac_f32_dpp v225, v101, v113 row_shr:1 row_mask:0xf bank_mask:0xf
	v_fmac_f32_dpp v226, v102, v114 row_shr:1 row_mask:0xf bank_mask:0xf
	v_fmac_f32_dpp v227, v103, v115 row_shr:1 row_mask:0xf bank_mask:0xf
	v_fmac_f32_dpp v224, v108, v112 row_shl:15 row_mask:0xf bank_mask:0xf
	v_fmac_f32_dpp v225, v109, v113 row_shl:15 row_mask:0xf bank_mask:0xf
	v_fmac_f32_dpp v226, v110, v114 row_shl:15 row_mask:0xf bank_mask:0xf
	v_fmac_f32_dpp v227, v111, v115 row_shl:15 row_mask:0xf bank_mask:0xf
	v_fmac_f32_dpp v224, v100, v120 row_shl:1 row_mask:0xf bank_mask:0xf
	v_fmac_f32_dpp v225, v101, v121 row_shl:1 row_mask:0xf bank_mask:0xf
	v_fmac_f32_dpp v226, v102, v122 row_shl:1 row_mask:0xf bank_mask:0xf
	v_fmac_f32_dpp v227, v103, v123 row_shl:1 row_mask:0xf bank_mask:0xf
	v_pk_fma_f32 v[228:229], v[136:137], v[96:97], v[144:145]
	v_pk_fma_f32 v[230:231], v[138:139], v[98:99], v[146:147]
	v_fmac_f32_dpp v228, v96, v132 row_shr:1 row_mask:0xf bank_mask:0xf
	v_fmac_f32_dpp v229, v97, v133 row_shr:1 row_mask:0xf bank_mask:0xf
	v_fmac_f32_dpp v230, v98, v134 row_shr:1 row_mask:0xf bank_mask:0xf
	v_fmac_f32_dpp v231, v99, v135 row_shr:1 row_mask:0xf bank_mask:0xf
	v_fmac_f32_dpp v228, v104, v132 row_shl:15 row_mask:0xf bank_mask:0xf
	v_fmac_f32_dpp v229, v105, v133 row_shl:15 row_mask:0xf bank_mask:0xf
	v_fmac_f32_dpp v230, v106, v134 row_shl:15 row_mask:0xf bank_mask:0xf
	v_fmac_f32_dpp v231, v107, v135 row_shl:15 row_mask:0xf bank_mask:0xf
	v_fmac_f32_dpp v228, v96, v140 row_shl:1 row_mask:0xf bank_mask:0xf
	v_fmac_f32_dpp v229, v97, v141 row_shl:1 row_mask:0xf bank_mask:0xf
	v_fmac_f32_dpp v230, v98, v142 row_shl:1 row_mask:0xf bank_mask:0xf
	v_fmac_f32_dpp v231, v99, v143 row_shl:1 row_mask:0xf bank_mask:0xf
	v_pk_mul_f32 v[232:233], v[224:225], v[238:239]
	v_pk_mul_f32 v[234:235], v[226:227], v[238:239]
	v_exp_f32_e32 v232, v232
	v_exp_f32_e32 v233, v233
	v_exp_f32_e32 v234, v234
	v_exp_f32_e32 v235, v235
	v_pk_add_f32 v[232:233], v[232:233], 1.0 op_sel_hi:[1,0]
	v_pk_add_f32 v[234:235], v[234:235], 1.0 op_sel_hi:[1,0]
	v_rcp_f32_e32 v232, v232
	v_rcp_f32_e32 v233, v233
	v_rcp_f32_e32 v234, v234
	v_rcp_f32_e32 v235, v235
	v_pk_mul_f32 v[224:225], v[224:225], v[232:233]
	v_pk_mul_f32 v[226:227], v[226:227], v[234:235]
	v_pk_mul_f32 v[224:225], v[224:225], v[228:229]
	v_pk_mul_f32 v[226:227], v[226:227], v[230:231]
	v_cvt_pk_bf16_f32 v236, v224, v225
	v_cvt_pk_bf16_f32 v237, v226, v227
	v_add_u32_e32 v213, 0x42000, v210
	global_store_dwordx2 v213, v[236:237], s[36:37]
	v_pk_fma_f32 v[224:225], v[116:117], v[92:93], v[124:125]
	v_pk_fma_f32 v[226:227], v[118:119], v[94:95], v[126:127]
	v_fmac_f32_dpp v224, v92, v112 row_shr:1 row_mask:0xf bank_mask:0xf
	v_fmac_f32_dpp v225, v93, v113 row_shr:1 row_mask:0xf bank_mask:0xf
	v_fmac_f32_dpp v226, v94, v114 row_shr:1 row_mask:0xf bank_mask:0xf
	v_fmac_f32_dpp v227, v95, v115 row_shr:1 row_mask:0xf bank_mask:0xf
	v_fmac_f32_dpp v224, v92, v120 row_shl:1 row_mask:0xf bank_mask:0xf
	v_fmac_f32_dpp v225, v93, v121 row_shl:1 row_mask:0xf bank_mask:0xf
	v_fmac_f32_dpp v226, v94, v122 row_shl:1 row_mask:0xf bank_mask:0xf
	v_fmac_f32_dpp v227, v95, v123 row_shl:1 row_mask:0xf bank_mask:0xf
	v_fmac_f32_dpp v224, v84, v120 row_shr:15 row_mask:0xf bank_mask:0xf
	v_fmac_f32_dpp v225, v85, v121 row_shr:15 row_mask:0xf bank_mask:0xf
	v_fmac_f32_dpp v226, v86, v122 row_shr:15 row_mask:0xf bank_mask:0xf
	v_fmac_f32_dpp v227, v87, v123 row_shr:15 row_mask:0xf bank_mask:0xf
	v_pk_fma_f32 v[228:229], v[136:137], v[88:89], v[144:145]
	v_pk_fma_f32 v[230:231], v[138:139], v[90:91], v[146:147]
	v_fmac_f32_dpp v228, v88, v132 row_shr:1 row_mask:0xf bank_mask:0xf
	v_fmac_f32_dpp v229, v89, v133 row_shr:1 row_mask:0xf bank_mask:0xf
	v_fmac_f32_dpp v230, v90, v134 row_shr:1 row_mask:0xf bank_mask:0xf
	v_fmac_f32_dpp v231, v91, v135 row_shr:1 row_mask:0xf bank_mask:0xf
	v_fmac_f32_dpp v228, v88, v140 row_shl:1 row_mask:0xf bank_mask:0xf
	v_fmac_f32_dpp v229, v89, v141 row_shl:1 row_mask:0xf bank_mask:0xf
	v_fmac_f32_dpp v230, v90, v142 row_shl:1 row_mask:0xf bank_mask:0xf
	v_fmac_f32_dpp v231, v91, v143 row_shl:1 row_mask:0xf bank_mask:0xf
	v_fmac_f32_dpp v228, v80, v140 row_shr:15 row_mask:0xf bank_mask:0xf
	v_fmac_f32_dpp v229, v81, v141 row_shr:15 row_mask:0xf bank_mask:0xf
	v_fmac_f32_dpp v230, v82, v142 row_shr:15 row_mask:0xf bank_mask:0xf
	v_fmac_f32_dpp v231, v83, v143 row_shr:15 row_mask:0xf bank_mask:0xf
	v_pk_mul_f32 v[232:233], v[224:225], v[238:239]
	v_pk_mul_f32 v[234:235], v[226:227], v[238:239]
	v_exp_f32_e32 v232, v232
	v_exp_f32_e32 v233, v233
	v_exp_f32_e32 v234, v234
	v_exp_f32_e32 v235, v235
	v_pk_add_f32 v[232:233], v[232:233], 1.0 op_sel_hi:[1,0]
	v_pk_add_f32 v[234:235], v[234:235], 1.0 op_sel_hi:[1,0]
	v_rcp_f32_e32 v232, v232
	v_rcp_f32_e32 v233, v233
	v_rcp_f32_e32 v234, v234
	v_rcp_f32_e32 v235, v235
	v_pk_mul_f32 v[224:225], v[224:225], v[232:233]
	v_pk_mul_f32 v[226:227], v[226:227], v[234:235]
	v_pk_mul_f32 v[224:225], v[224:225], v[228:229]
	v_pk_mul_f32 v[226:227], v[226:227], v[230:231]
	v_cvt_pk_bf16_f32 v236, v224, v225
	v_cvt_pk_bf16_f32 v237, v226, v227
	v_add_u32_e32 v213, 0xb0000, v210
	global_store_dwordx2 v213, v[236:237], s[36:37]
	v_pk_fma_f32 v[224:225], v[116:117], v[84:85], v[124:125]
	v_pk_fma_f32 v[226:227], v[118:119], v[86:87], v[126:127]
	v_fmac_f32_dpp v224, v84, v112 row_shr:1 row_mask:0xf bank_mask:0xf
	v_fmac_f32_dpp v225, v85, v113 row_shr:1 row_mask:0xf bank_mask:0xf
	v_fmac_f32_dpp v226, v86, v114 row_shr:1 row_mask:0xf bank_mask:0xf
	v_fmac_f32_dpp v227, v87, v115 row_shr:1 row_mask:0xf bank_mask:0xf
	v_fmac_f32_dpp v224, v92, v112 row_shl:15 row_mask:0xf bank_mask:0xf
	v_fmac_f32_dpp v225, v93, v113 row_shl:15 row_mask:0xf bank_mask:0xf
	v_fmac_f32_dpp v226, v94, v114 row_shl:15 row_mask:0xf bank_mask:0xf
	v_fmac_f32_dpp v227, v95, v115 row_shl:15 row_mask:0xf bank_mask:0xf
	v_fmac_f32_dpp v224, v84, v120 row_shl:1 row_mask:0xf bank_mask:0xf
	v_fmac_f32_dpp v225, v85, v121 row_shl:1 row_mask:0xf bank_mask:0xf
	v_fmac_f32_dpp v226, v86, v122 row_shl:1 row_mask:0xf bank_mask:0xf
	v_fmac_f32_dpp v227, v87, v123 row_shl:1 row_mask:0xf bank_mask:0xf
	v_fmac_f32_dpp v224, v76, v120 row_shr:15 row_mask:0xf bank_mask:0xf
	v_fmac_f32_dpp v225, v77, v121 row_shr:15 row_mask:0xf bank_mask:0xf
	v_fmac_f32_dpp v226, v78, v122 row_shr:15 row_mask:0xf bank_mask:0xf
	v_fmac_f32_dpp v227, v79, v123 row_shr:15 row_mask:0xf bank_mask:0xf
	v_pk_fma_f32 v[228:229], v[136:137], v[80:81], v[144:145]
	v_pk_fma_f32 v[230:231], v[138:139], v[82:83], v[146:147]
	v_fmac_f32_dpp v228, v80, v132 row_shr:1 row_mask:0xf bank_mask:0xf
	v_fmac_f32_dpp v229, v81, v133 row_shr:1 row_mask:0xf bank_mask:0xf
	v_fmac_f32_dpp v230, v82, v134 row_shr:1 row_mask:0xf bank_mask:0xf
	v_fmac_f32_dpp v231, v83, v135 row_shr:1 row_mask:0xf bank_mask:0xf
	v_fmac_f32_dpp v228, v88, v132 row_shl:15 row_mask:0xf bank_mask:0xf
	v_fmac_f32_dpp v229, v89, v133 row_shl:15 row_mask:0xf bank_mask:0xf
	v_fmac_f32_dpp v230, v90, v134 row_shl:15 row_mask:0xf bank_mask:0xf
	v_fmac_f32_dpp v231, v91, v135 row_shl:15 row_mask:0xf bank_mask:0xf
	v_fmac_f32_dpp v228, v80, v140 row_shl:1 row_mask:0xf bank_mask:0xf
	v_fmac_f32_dpp v229, v81, v141 row_shl:1 row_mask:0xf bank_mask:0xf
	v_fmac_f32_dpp v230, v82, v142 row_shl:1 row_mask:0xf bank_mask:0xf
	v_fmac_f32_dpp v231, v83, v143 row_shl:1 row_mask:0xf bank_mask:0xf
	v_fmac_f32_dpp v228, v72, v140 row_shr:15 row_mask:0xf bank_mask:0xf
	v_fmac_f32_dpp v229, v73, v141 row_shr:15 row_mask:0xf bank_mask:0xf
	v_fmac_f32_dpp v230, v74, v142 row_shr:15 row_mask:0xf bank_mask:0xf
	v_fmac_f32_dpp v231, v75, v143 row_shr:15 row_mask:0xf bank_mask:0xf
	v_pk_mul_f32 v[232:233], v[224:225], v[238:239]
	v_pk_mul_f32 v[234:235], v[226:227], v[238:239]
	v_exp_f32_e32 v232, v232
	v_exp_f32_e32 v233, v233
	v_exp_f32_e32 v234, v234
	v_exp_f32_e32 v235, v235
	v_pk_add_f32 v[232:233], v[232:233], 1.0 op_sel_hi:[1,0]
	v_pk_add_f32 v[234:235], v[234:235], 1.0 op_sel_hi:[1,0]
	v_rcp_f32_e32 v232, v232
	v_rcp_f32_e32 v233, v233
	v_rcp_f32_e32 v234, v234
	v_rcp_f32_e32 v235, v235
	v_pk_mul_f32 v[224:225], v[224:225], v[232:233]
	v_pk_mul_f32 v[226:227], v[226:227], v[234:235]
	v_pk_mul_f32 v[224:225], v[224:225], v[228:229]
	v_pk_mul_f32 v[226:227], v[226:227], v[230:231]
	v_cvt_pk_bf16_f32 v236, v224, v225
	v_cvt_pk_bf16_f32 v237, v226, v227
	v_add_u32_e32 v213, 0xc6000, v210
	global_store_dwordx2 v213, v[236:237], s[36:37]
	v_pk_fma_f32 v[224:225], v[116:117], v[76:77], v[124:125]
	v_pk_fma_f32 v[226:227], v[118:119], v[78:79], v[126:127]
	v_fmac_f32_dpp v224, v76, v112 row_shr:1 row_mask:0xf bank_mask:0xf
	v_fmac_f32_dpp v225, v77, v113 row_shr:1 row_mask:0xf bank_mask:0xf
	v_fmac_f32_dpp v226, v78, v114 row_shr:1 row_mask:0xf bank_mask:0xf
	v_fmac_f32_dpp v227, v79, v115 row_shr:1 row_mask:0xf bank_mask:0xf
	v_fmac_f32_dpp v224, v84, v112 row_shl:15 row_mask:0xf bank_mask:0xf
	v_fmac_f32_dpp v225, v85, v113 row_shl:15 row_mask:0xf bank_mask:0xf
	v_fmac_f32_dpp v226, v86, v114 row_shl:15 row_mask:0xf bank_mask:0xf
	v_fmac_f32_dpp v227, v87, v115 row_shl:15 row_mask:0xf bank_mask:0xf
	v_fmac_f32_dpp v224, v76, v120 row_shl:1 row_mask:0xf bank_mask:0xf
	v_fmac_f32_dpp v225, v77, v121 row_shl:1 row_mask:0xf bank_mask:0xf
	v_fmac_f32_dpp v226, v78, v122 row_shl:1 row_mask:0xf bank_mask:0xf
	v_fmac_f32_dpp v227, v79, v123 row_shl:1 row_mask:0xf bank_mask:0xf
	v_fmac_f32_dpp v224, v68, v120 row_shr:15 row_mask:0xf bank_mask:0xf
	v_fmac_f32_dpp v225, v69, v121 row_shr:15 row_mask:0xf bank_mask:0xf
	v_fmac_f32_dpp v226, v70, v122 row_shr:15 row_mask:0xf bank_mask:0xf
	v_fmac_f32_dpp v227, v71, v123 row_shr:15 row_mask:0xf bank_mask:0xf
	v_pk_fma_f32 v[228:229], v[136:137], v[72:73], v[144:145]
	v_pk_fma_f32 v[230:231], v[138:139], v[74:75], v[146:147]
	v_fmac_f32_dpp v228, v72, v132 row_shr:1 row_mask:0xf bank_mask:0xf
	v_fmac_f32_dpp v229, v73, v133 row_shr:1 row_mask:0xf bank_mask:0xf
	v_fmac_f32_dpp v230, v74, v134 row_shr:1 row_mask:0xf bank_mask:0xf
	v_fmac_f32_dpp v231, v75, v135 row_shr:1 row_mask:0xf bank_mask:0xf
	v_fmac_f32_dpp v228, v80, v132 row_shl:15 row_mask:0xf bank_mask:0xf
	v_fmac_f32_dpp v229, v81, v133 row_shl:15 row_mask:0xf bank_mask:0xf
	v_fmac_f32_dpp v230, v82, v134 row_shl:15 row_mask:0xf bank_mask:0xf
	v_fmac_f32_dpp v231, v83, v135 row_shl:15 row_mask:0xf bank_mask:0xf
	v_fmac_f32_dpp v228, v72, v140 row_shl:1 row_mask:0xf bank_mask:0xf
	v_fmac_f32_dpp v229, v73, v141 row_shl:1 row_mask:0xf bank_mask:0xf
	v_fmac_f32_dpp v230, v74, v142 row_shl:1 row_mask:0xf bank_mask:0xf
	v_fmac_f32_dpp v231, v75, v143 row_shl:1 row_mask:0xf bank_mask:0xf
	v_fmac_f32_dpp v228, v64, v140 row_shr:15 row_mask:0xf bank_mask:0xf
	v_fmac_f32_dpp v229, v65, v141 row_shr:15 row_mask:0xf bank_mask:0xf
	v_fmac_f32_dpp v230, v66, v142 row_shr:15 row_mask:0xf bank_mask:0xf
	v_fmac_f32_dpp v231, v67, v143 row_shr:15 row_mask:0xf bank_mask:0xf
	v_pk_mul_f32 v[232:233], v[224:225], v[238:239]
	v_pk_mul_f32 v[234:235], v[226:227], v[238:239]
	v_exp_f32_e32 v232, v232
	v_exp_f32_e32 v233, v233
	v_exp_f32_e32 v234, v234
	v_exp_f32_e32 v235, v235
	v_pk_add_f32 v[232:233], v[232:233], 1.0 op_sel_hi:[1,0]
	v_pk_add_f32 v[234:235], v[234:235], 1.0 op_sel_hi:[1,0]
	v_rcp_f32_e32 v232, v232
	v_rcp_f32_e32 v233, v233
	v_rcp_f32_e32 v234, v234
	v_rcp_f32_e32 v235, v235
	v_pk_mul_f32 v[224:225], v[224:225], v[232:233]
	v_pk_mul_f32 v[226:227], v[226:227], v[234:235]
	v_pk_mul_f32 v[224:225], v[224:225], v[228:229]
	v_pk_mul_f32 v[226:227], v[226:227], v[230:231]
	v_cvt_pk_bf16_f32 v236, v224, v225
	v_cvt_pk_bf16_f32 v237, v226, v227
	v_add_u32_e32 v213, 0xdc000, v210
	global_store_dwordx2 v213, v[236:237], s[36:37]
	v_pk_fma_f32 v[224:225], v[116:117], v[68:69], v[124:125]
	v_pk_fma_f32 v[226:227], v[118:119], v[70:71], v[126:127]
	v_fmac_f32_dpp v224, v68, v112 row_shr:1 row_mask:0xf bank_mask:0xf
	v_fmac_f32_dpp v225, v69, v113 row_shr:1 row_mask:0xf bank_mask:0xf
	v_fmac_f32_dpp v226, v70, v114 row_shr:1 row_mask:0xf bank_mask:0xf
	v_fmac_f32_dpp v227, v71, v115 row_shr:1 row_mask:0xf bank_mask:0xf
	v_fmac_f32_dpp v224, v76, v112 row_shl:15 row_mask:0xf bank_mask:0xf
	v_fmac_f32_dpp v225, v77, v113 row_shl:15 row_mask:0xf bank_mask:0xf
	v_fmac_f32_dpp v226, v78, v114 row_shl:15 row_mask:0xf bank_mask:0xf
	v_fmac_f32_dpp v227, v79, v115 row_shl:15 row_mask:0xf bank_mask:0xf
	v_fmac_f32_dpp v224, v68, v120 row_shl:1 row_mask:0xf bank_mask:0xf
	v_fmac_f32_dpp v225, v69, v121 row_shl:1 row_mask:0xf bank_mask:0xf
	v_fmac_f32_dpp v226, v70, v122 row_shl:1 row_mask:0xf bank_mask:0xf
	v_fmac_f32_dpp v227, v71, v123 row_shl:1 row_mask:0xf bank_mask:0xf
	v_pk_fma_f32 v[228:229], v[136:137], v[64:65], v[144:145]
	v_pk_fma_f32 v[230:231], v[138:139], v[66:67], v[146:147]
	v_fmac_f32_dpp v228, v64, v132 row_shr:1 row_mask:0xf bank_mask:0xf
	v_fmac_f32_dpp v229, v65, v133 row_shr:1 row_mask:0xf bank_mask:0xf
	v_fmac_f32_dpp v230, v66, v134 row_shr:1 row_mask:0xf bank_mask:0xf
	v_fmac_f32_dpp v231, v67, v135 row_shr:1 row_mask:0xf bank_mask:0xf
	v_fmac_f32_dpp v228, v72, v132 row_shl:15 row_mask:0xf bank_mask:0xf
	v_fmac_f32_dpp v229, v73, v133 row_shl:15 row_mask:0xf bank_mask:0xf
	v_fmac_f32_dpp v230, v74, v134 row_shl:15 row_mask:0xf bank_mask:0xf
	v_fmac_f32_dpp v231, v75, v135 row_shl:15 row_mask:0xf bank_mask:0xf
	v_fmac_f32_dpp v228, v64, v140 row_shl:1 row_mask:0xf bank_mask:0xf
	v_fmac_f32_dpp v229, v65, v141 row_shl:1 row_mask:0xf bank_mask:0xf
	v_fmac_f32_dpp v230, v66, v142 row_shl:1 row_mask:0xf bank_mask:0xf
	v_fmac_f32_dpp v231, v67, v143 row_shl:1 row_mask:0xf bank_mask:0xf
	v_pk_mul_f32 v[232:233], v[224:225], v[238:239]
	v_pk_mul_f32 v[234:235], v[226:227], v[238:239]
	v_exp_f32_e32 v232, v232
	v_exp_f32_e32 v233, v233
	v_exp_f32_e32 v234, v234
	v_exp_f32_e32 v235, v235
	v_pk_add_f32 v[232:233], v[232:233], 1.0 op_sel_hi:[1,0]
	v_pk_add_f32 v[234:235], v[234:235], 1.0 op_sel_hi:[1,0]
	v_rcp_f32_e32 v232, v232
	v_rcp_f32_e32 v233, v233
	v_rcp_f32_e32 v234, v234
	v_rcp_f32_e32 v235, v235
	v_pk_mul_f32 v[224:225], v[224:225], v[232:233]
	v_pk_mul_f32 v[226:227], v[226:227], v[234:235]
	v_pk_mul_f32 v[224:225], v[224:225], v[228:229]
	v_pk_mul_f32 v[226:227], v[226:227], v[230:231]
	v_cvt_pk_bf16_f32 v236, v224, v225
	v_cvt_pk_bf16_f32 v237, v226, v227
	v_add_u32_e32 v213, 0xf2000, v210
	global_store_dwordx2 v213, v[236:237], s[36:37]
	v_pk_fma_f32 v[224:225], v[180:181], v[60:61], v[188:189]
	v_pk_fma_f32 v[226:227], v[182:183], v[62:63], v[190:191]
	v_fmac_f32_dpp v224, v60, v176 row_shr:1 row_mask:0xf bank_mask:0xf
	v_fmac_f32_dpp v225, v61, v177 row_shr:1 row_mask:0xf bank_mask:0xf
	v_fmac_f32_dpp v226, v62, v178 row_shr:1 row_mask:0xf bank_mask:0xf
	v_fmac_f32_dpp v227, v63, v179 row_shr:1 row_mask:0xf bank_mask:0xf
	v_fmac_f32_dpp v224, v60, v184 row_shl:1 row_mask:0xf bank_mask:0xf
	v_fmac_f32_dpp v225, v61, v185 row_shl:1 row_mask:0xf bank_mask:0xf
	v_fmac_f32_dpp v226, v62, v186 row_shl:1 row_mask:0xf bank_mask:0xf
	v_fmac_f32_dpp v227, v63, v187 row_shl:1 row_mask:0xf bank_mask:0xf
	v_fmac_f32_dpp v224, v52, v184 row_shr:15 row_mask:0xf bank_mask:0xf
	v_fmac_f32_dpp v225, v53, v185 row_shr:15 row_mask:0xf bank_mask:0xf
	v_fmac_f32_dpp v226, v54, v186 row_shr:15 row_mask:0xf bank_mask:0xf
	v_fmac_f32_dpp v227, v55, v187 row_shr:15 row_mask:0xf bank_mask:0xf
	v_pk_fma_f32 v[228:229], v[196:197], v[56:57], v[204:205]
	v_pk_fma_f32 v[230:231], v[198:199], v[58:59], v[206:207]
	v_fmac_f32_dpp v228, v56, v192 row_shr:1 row_mask:0xf bank_mask:0xf
	v_fmac_f32_dpp v229, v57, v193 row_shr:1 row_mask:0xf bank_mask:0xf
	v_fmac_f32_dpp v230, v58, v194 row_shr:1 row_mask:0xf bank_mask:0xf
	v_fmac_f32_dpp v231, v59, v195 row_shr:1 row_mask:0xf bank_mask:0xf
	v_fmac_f32_dpp v228, v56, v200 row_shl:1 row_mask:0xf bank_mask:0xf
	v_fmac_f32_dpp v229, v57, v201 row_shl:1 row_mask:0xf bank_mask:0xf
	v_fmac_f32_dpp v230, v58, v202 row_shl:1 row_mask:0xf bank_mask:0xf
	v_fmac_f32_dpp v231, v59, v203 row_shl:1 row_mask:0xf bank_mask:0xf
	v_fmac_f32_dpp v228, v48, v200 row_shr:15 row_mask:0xf bank_mask:0xf
	v_fmac_f32_dpp v229, v49, v201 row_shr:15 row_mask:0xf bank_mask:0xf
	v_fmac_f32_dpp v230, v50, v202 row_shr:15 row_mask:0xf bank_mask:0xf
	v_fmac_f32_dpp v231, v51, v203 row_shr:15 row_mask:0xf bank_mask:0xf
	v_pk_mul_f32 v[232:233], v[224:225], v[238:239]
	v_pk_mul_f32 v[234:235], v[226:227], v[238:239]
	v_exp_f32_e32 v232, v232
	v_exp_f32_e32 v233, v233
	v_exp_f32_e32 v234, v234
	v_exp_f32_e32 v235, v235
	v_pk_add_f32 v[232:233], v[232:233], 1.0 op_sel_hi:[1,0]
	v_pk_add_f32 v[234:235], v[234:235], 1.0 op_sel_hi:[1,0]
	v_rcp_f32_e32 v232, v232
	v_rcp_f32_e32 v233, v233
	v_rcp_f32_e32 v234, v234
	v_rcp_f32_e32 v235, v235
	v_pk_mul_f32 v[224:225], v[224:225], v[232:233]
	v_pk_mul_f32 v[226:227], v[226:227], v[234:235]
	v_pk_mul_f32 v[224:225], v[224:225], v[228:229]
	v_pk_mul_f32 v[226:227], v[226:227], v[230:231]
	v_cvt_pk_bf16_f32 v236, v224, v225
	v_cvt_pk_bf16_f32 v237, v226, v227
	global_store_dwordx2 v210, v[236:237], s[36:37] offset:8
	v_pk_fma_f32 v[224:225], v[180:181], v[52:53], v[188:189]
	v_pk_fma_f32 v[226:227], v[182:183], v[54:55], v[190:191]
	v_fmac_f32_dpp v224, v52, v176 row_shr:1 row_mask:0xf bank_mask:0xf
	v_fmac_f32_dpp v225, v53, v177 row_shr:1 row_mask:0xf bank_mask:0xf
	v_fmac_f32_dpp v226, v54, v178 row_shr:1 row_mask:0xf bank_mask:0xf
	v_fmac_f32_dpp v227, v55, v179 row_shr:1 row_mask:0xf bank_mask:0xf
	v_fmac_f32_dpp v224, v60, v176 row_shl:15 row_mask:0xf bank_mask:0xf
	v_fmac_f32_dpp v225, v61, v177 row_shl:15 row_mask:0xf bank_mask:0xf
	v_fmac_f32_dpp v226, v62, v178 row_shl:15 row_mask:0xf bank_mask:0xf
	v_fmac_f32_dpp v227, v63, v179 row_shl:15 row_mask:0xf bank_mask:0xf
	v_fmac_f32_dpp v224, v52, v184 row_shl:1 row_mask:0xf bank_mask:0xf
	v_fmac_f32_dpp v225, v53, v185 row_shl:1 row_mask:0xf bank_mask:0xf
	v_fmac_f32_dpp v226, v54, v186 row_shl:1 row_mask:0xf bank_mask:0xf
	v_fmac_f32_dpp v227, v55, v187 row_shl:1 row_mask:0xf bank_mask:0xf
	v_fmac_f32_dpp v224, v44, v184 row_shr:15 row_mask:0xf bank_mask:0xf
	v_fmac_f32_dpp v225, v45, v185 row_shr:15 row_mask:0xf bank_mask:0xf
	v_fmac_f32_dpp v226, v46, v186 row_shr:15 row_mask:0xf bank_mask:0xf
	v_fmac_f32_dpp v227, v47, v187 row_shr:15 row_mask:0xf bank_mask:0xf
	v_pk_fma_f32 v[228:229], v[196:197], v[48:49], v[204:205]
	v_pk_fma_f32 v[230:231], v[198:199], v[50:51], v[206:207]
	v_fmac_f32_dpp v228, v48, v192 row_shr:1 row_mask:0xf bank_mask:0xf
	v_fmac_f32_dpp v229, v49, v193 row_shr:1 row_mask:0xf bank_mask:0xf
	v_fmac_f32_dpp v230, v50, v194 row_shr:1 row_mask:0xf bank_mask:0xf
	v_fmac_f32_dpp v231, v51, v195 row_shr:1 row_mask:0xf bank_mask:0xf
	v_fmac_f32_dpp v228, v56, v192 row_shl:15 row_mask:0xf bank_mask:0xf
	v_fmac_f32_dpp v229, v57, v193 row_shl:15 row_mask:0xf bank_mask:0xf
	v_fmac_f32_dpp v230, v58, v194 row_shl:15 row_mask:0xf bank_mask:0xf
	v_fmac_f32_dpp v231, v59, v195 row_shl:15 row_mask:0xf bank_mask:0xf
	v_fmac_f32_dpp v228, v48, v200 row_shl:1 row_mask:0xf bank_mask:0xf
	v_fmac_f32_dpp v229, v49, v201 row_shl:1 row_mask:0xf bank_mask:0xf
	v_fmac_f32_dpp v230, v50, v202 row_shl:1 row_mask:0xf bank_mask:0xf
	v_fmac_f32_dpp v231, v51, v203 row_shl:1 row_mask:0xf bank_mask:0xf
	v_fmac_f32_dpp v228, v40, v200 row_shr:15 row_mask:0xf bank_mask:0xf
	v_fmac_f32_dpp v229, v41, v201 row_shr:15 row_mask:0xf bank_mask:0xf
	v_fmac_f32_dpp v230, v42, v202 row_shr:15 row_mask:0xf bank_mask:0xf
	v_fmac_f32_dpp v231, v43, v203 row_shr:15 row_mask:0xf bank_mask:0xf
	v_pk_mul_f32 v[232:233], v[224:225], v[238:239]
	v_pk_mul_f32 v[234:235], v[226:227], v[238:239]
	v_exp_f32_e32 v232, v232
	v_exp_f32_e32 v233, v233
	v_exp_f32_e32 v234, v234
	v_exp_f32_e32 v235, v235
	v_pk_add_f32 v[232:233], v[232:233], 1.0 op_sel_hi:[1,0]
	v_pk_add_f32 v[234:235], v[234:235], 1.0 op_sel_hi:[1,0]
	v_rcp_f32_e32 v232, v232
	v_rcp_f32_e32 v233, v233
	v_rcp_f32_e32 v234, v234
	v_rcp_f32_e32 v235, v235
	v_pk_mul_f32 v[224:225], v[224:225], v[232:233]
	v_pk_mul_f32 v[226:227], v[226:227], v[234:235]
	v_pk_mul_f32 v[224:225], v[224:225], v[228:229]
	v_pk_mul_f32 v[226:227], v[226:227], v[230:231]
	v_cvt_pk_bf16_f32 v236, v224, v225
	v_cvt_pk_bf16_f32 v237, v226, v227
	v_add_u32_e32 v213, 0x16000, v210
	global_store_dwordx2 v213, v[236:237], s[36:37] offset:8
	v_pk_fma_f32 v[224:225], v[180:181], v[44:45], v[188:189]
	v_pk_fma_f32 v[226:227], v[182:183], v[46:47], v[190:191]
	v_fmac_f32_dpp v224, v44, v176 row_shr:1 row_mask:0xf bank_mask:0xf
	v_fmac_f32_dpp v225, v45, v177 row_shr:1 row_mask:0xf bank_mask:0xf
	v_fmac_f32_dpp v226, v46, v178 row_shr:1 row_mask:0xf bank_mask:0xf
	v_fmac_f32_dpp v227, v47, v179 row_shr:1 row_mask:0xf bank_mask:0xf
	v_fmac_f32_dpp v224, v52, v176 row_shl:15 row_mask:0xf bank_mask:0xf
	v_fmac_f32_dpp v225, v53, v177 row_shl:15 row_mask:0xf bank_mask:0xf
	v_fmac_f32_dpp v226, v54, v178 row_shl:15 row_mask:0xf bank_mask:0xf
	v_fmac_f32_dpp v227, v55, v179 row_shl:15 row_mask:0xf bank_mask:0xf
	v_fmac_f32_dpp v224, v44, v184 row_shl:1 row_mask:0xf bank_mask:0xf
	v_fmac_f32_dpp v225, v45, v185 row_shl:1 row_mask:0xf bank_mask:0xf
	v_fmac_f32_dpp v226, v46, v186 row_shl:1 row_mask:0xf bank_mask:0xf
	v_fmac_f32_dpp v227, v47, v187 row_shl:1 row_mask:0xf bank_mask:0xf
	v_fmac_f32_dpp v224, v36, v184 row_shr:15 row_mask:0xf bank_mask:0xf
	v_fmac_f32_dpp v225, v37, v185 row_shr:15 row_mask:0xf bank_mask:0xf
	v_fmac_f32_dpp v226, v38, v186 row_shr:15 row_mask:0xf bank_mask:0xf
	v_fmac_f32_dpp v227, v39, v187 row_shr:15 row_mask:0xf bank_mask:0xf
	v_pk_fma_f32 v[228:229], v[196:197], v[40:41], v[204:205]
	v_pk_fma_f32 v[230:231], v[198:199], v[42:43], v[206:207]
	v_fmac_f32_dpp v228, v40, v192 row_shr:1 row_mask:0xf bank_mask:0xf
	v_fmac_f32_dpp v229, v41, v193 row_shr:1 row_mask:0xf bank_mask:0xf
	v_fmac_f32_dpp v230, v42, v194 row_shr:1 row_mask:0xf bank_mask:0xf
	v_fmac_f32_dpp v231, v43, v195 row_shr:1 row_mask:0xf bank_mask:0xf
	v_fmac_f32_dpp v228, v48, v192 row_shl:15 row_mask:0xf bank_mask:0xf
	v_fmac_f32_dpp v229, v49, v193 row_shl:15 row_mask:0xf bank_mask:0xf
	v_fmac_f32_dpp v230, v50, v194 row_shl:15 row_mask:0xf bank_mask:0xf
	v_fmac_f32_dpp v231, v51, v195 row_shl:15 row_mask:0xf bank_mask:0xf
	v_fmac_f32_dpp v228, v40, v200 row_shl:1 row_mask:0xf bank_mask:0xf
	v_fmac_f32_dpp v229, v41, v201 row_shl:1 row_mask:0xf bank_mask:0xf
	v_fmac_f32_dpp v230, v42, v202 row_shl:1 row_mask:0xf bank_mask:0xf
	v_fmac_f32_dpp v231, v43, v203 row_shl:1 row_mask:0xf bank_mask:0xf
	v_fmac_f32_dpp v228, v32, v200 row_shr:15 row_mask:0xf bank_mask:0xf
	v_fmac_f32_dpp v229, v33, v201 row_shr:15 row_mask:0xf bank_mask:0xf
	v_fmac_f32_dpp v230, v34, v202 row_shr:15 row_mask:0xf bank_mask:0xf
	v_fmac_f32_dpp v231, v35, v203 row_shr:15 row_mask:0xf bank_mask:0xf
	v_pk_mul_f32 v[232:233], v[224:225], v[238:239]
	v_pk_mul_f32 v[234:235], v[226:227], v[238:239]
	v_exp_f32_e32 v232, v232
	v_exp_f32_e32 v233, v233
	v_exp_f32_e32 v234, v234
	v_exp_f32_e32 v235, v235
	v_pk_add_f32 v[232:233], v[232:233], 1.0 op_sel_hi:[1,0]
	v_pk_add_f32 v[234:235], v[234:235], 1.0 op_sel_hi:[1,0]
	v_rcp_f32_e32 v232, v232
	v_rcp_f32_e32 v233, v233
	v_rcp_f32_e32 v234, v234
	v_rcp_f32_e32 v235, v235
	v_pk_mul_f32 v[224:225], v[224:225], v[232:233]
	v_pk_mul_f32 v[226:227], v[226:227], v[234:235]
	v_pk_mul_f32 v[224:225], v[224:225], v[228:229]
	v_pk_mul_f32 v[226:227], v[226:227], v[230:231]
	v_cvt_pk_bf16_f32 v236, v224, v225
	v_cvt_pk_bf16_f32 v237, v226, v227
	v_add_u32_e32 v213, 0x2c000, v210
	global_store_dwordx2 v213, v[236:237], s[36:37] offset:8
	v_pk_fma_f32 v[224:225], v[180:181], v[36:37], v[188:189]
	v_pk_fma_f32 v[226:227], v[182:183], v[38:39], v[190:191]
	v_fmac_f32_dpp v224, v36, v176 row_shr:1 row_mask:0xf bank_mask:0xf
	v_fmac_f32_dpp v225, v37, v177 row_shr:1 row_mask:0xf bank_mask:0xf
	v_fmac_f32_dpp v226, v38, v178 row_shr:1 row_mask:0xf bank_mask:0xf
	v_fmac_f32_dpp v227, v39, v179 row_shr:1 row_mask:0xf bank_mask:0xf
	v_fmac_f32_dpp v224, v44, v176 row_shl:15 row_mask:0xf bank_mask:0xf
	v_fmac_f32_dpp v225, v45, v177 row_shl:15 row_mask:0xf bank_mask:0xf
	v_fmac_f32_dpp v226, v46, v178 row_shl:15 row_mask:0xf bank_mask:0xf
	v_fmac_f32_dpp v227, v47, v179 row_shl:15 row_mask:0xf bank_mask:0xf
	v_fmac_f32_dpp v224, v36, v184 row_shl:1 row_mask:0xf bank_mask:0xf
	v_fmac_f32_dpp v225, v37, v185 row_shl:1 row_mask:0xf bank_mask:0xf
	v_fmac_f32_dpp v226, v38, v186 row_shl:1 row_mask:0xf bank_mask:0xf
	v_fmac_f32_dpp v227, v39, v187 row_shl:1 row_mask:0xf bank_mask:0xf
	v_pk_fma_f32 v[228:229], v[196:197], v[32:33], v[204:205]
	v_pk_fma_f32 v[230:231], v[198:199], v[34:35], v[206:207]
	v_fmac_f32_dpp v228, v32, v192 row_shr:1 row_mask:0xf bank_mask:0xf
	v_fmac_f32_dpp v229, v33, v193 row_shr:1 row_mask:0xf bank_mask:0xf
	v_fmac_f32_dpp v230, v34, v194 row_shr:1 row_mask:0xf bank_mask:0xf
	v_fmac_f32_dpp v231, v35, v195 row_shr:1 row_mask:0xf bank_mask:0xf
	v_fmac_f32_dpp v228, v40, v192 row_shl:15 row_mask:0xf bank_mask:0xf
	v_fmac_f32_dpp v229, v41, v193 row_shl:15 row_mask:0xf bank_mask:0xf
	v_fmac_f32_dpp v230, v42, v194 row_shl:15 row_mask:0xf bank_mask:0xf
	v_fmac_f32_dpp v231, v43, v195 row_shl:15 row_mask:0xf bank_mask:0xf
	v_fmac_f32_dpp v228, v32, v200 row_shl:1 row_mask:0xf bank_mask:0xf
	v_fmac_f32_dpp v229, v33, v201 row_shl:1 row_mask:0xf bank_mask:0xf
	v_fmac_f32_dpp v230, v34, v202 row_shl:1 row_mask:0xf bank_mask:0xf
	v_fmac_f32_dpp v231, v35, v203 row_shl:1 row_mask:0xf bank_mask:0xf
	v_pk_mul_f32 v[232:233], v[224:225], v[238:239]
	v_pk_mul_f32 v[234:235], v[226:227], v[238:239]
	v_exp_f32_e32 v232, v232
	v_exp_f32_e32 v233, v233
	v_exp_f32_e32 v234, v234
	v_exp_f32_e32 v235, v235
	v_pk_add_f32 v[232:233], v[232:233], 1.0 op_sel_hi:[1,0]
	v_pk_add_f32 v[234:235], v[234:235], 1.0 op_sel_hi:[1,0]
	v_rcp_f32_e32 v232, v232
	v_rcp_f32_e32 v233, v233
	v_rcp_f32_e32 v234, v234
	v_rcp_f32_e32 v235, v235
	v_pk_mul_f32 v[224:225], v[224:225], v[232:233]
	v_pk_mul_f32 v[226:227], v[226:227], v[234:235]
	v_pk_mul_f32 v[224:225], v[224:225], v[228:229]
	v_pk_mul_f32 v[226:227], v[226:227], v[230:231]
	v_cvt_pk_bf16_f32 v236, v224, v225
	v_cvt_pk_bf16_f32 v237, v226, v227
	v_add_u32_e32 v213, 0x42000, v210
	global_store_dwordx2 v213, v[236:237], s[36:37] offset:8
	v_pk_fma_f32 v[224:225], v[180:181], v[28:29], v[188:189]
	v_pk_fma_f32 v[226:227], v[182:183], v[30:31], v[190:191]
	v_fmac_f32_dpp v224, v28, v176 row_shr:1 row_mask:0xf bank_mask:0xf
	v_fmac_f32_dpp v225, v29, v177 row_shr:1 row_mask:0xf bank_mask:0xf
	v_fmac_f32_dpp v226, v30, v178 row_shr:1 row_mask:0xf bank_mask:0xf
	v_fmac_f32_dpp v227, v31, v179 row_shr:1 row_mask:0xf bank_mask:0xf
	v_fmac_f32_dpp v224, v28, v184 row_shl:1 row_mask:0xf bank_mask:0xf
	v_fmac_f32_dpp v225, v29, v185 row_shl:1 row_mask:0xf bank_mask:0xf
	v_fmac_f32_dpp v226, v30, v186 row_shl:1 row_mask:0xf bank_mask:0xf
	v_fmac_f32_dpp v227, v31, v187 row_shl:1 row_mask:0xf bank_mask:0xf
	v_fmac_f32_dpp v224, v20, v184 row_shr:15 row_mask:0xf bank_mask:0xf
	v_fmac_f32_dpp v225, v21, v185 row_shr:15 row_mask:0xf bank_mask:0xf
	v_fmac_f32_dpp v226, v22, v186 row_shr:15 row_mask:0xf bank_mask:0xf
	v_fmac_f32_dpp v227, v23, v187 row_shr:15 row_mask:0xf bank_mask:0xf
	v_pk_fma_f32 v[228:229], v[196:197], v[24:25], v[204:205]
	v_pk_fma_f32 v[230:231], v[198:199], v[26:27], v[206:207]
	v_fmac_f32_dpp v228, v24, v192 row_shr:1 row_mask:0xf bank_mask:0xf
	v_fmac_f32_dpp v229, v25, v193 row_shr:1 row_mask:0xf bank_mask:0xf
	v_fmac_f32_dpp v230, v26, v194 row_shr:1 row_mask:0xf bank_mask:0xf
	v_fmac_f32_dpp v231, v27, v195 row_shr:1 row_mask:0xf bank_mask:0xf
	v_fmac_f32_dpp v228, v24, v200 row_shl:1 row_mask:0xf bank_mask:0xf
	v_fmac_f32_dpp v229, v25, v201 row_shl:1 row_mask:0xf bank_mask:0xf
	v_fmac_f32_dpp v230, v26, v202 row_shl:1 row_mask:0xf bank_mask:0xf
	v_fmac_f32_dpp v231, v27, v203 row_shl:1 row_mask:0xf bank_mask:0xf
	v_fmac_f32_dpp v228, v16, v200 row_shr:15 row_mask:0xf bank_mask:0xf
	v_fmac_f32_dpp v229, v17, v201 row_shr:15 row_mask:0xf bank_mask:0xf
	v_fmac_f32_dpp v230, v18, v202 row_shr:15 row_mask:0xf bank_mask:0xf
	v_fmac_f32_dpp v231, v19, v203 row_shr:15 row_mask:0xf bank_mask:0xf
	v_pk_mul_f32 v[232:233], v[224:225], v[238:239]
	v_pk_mul_f32 v[234:235], v[226:227], v[238:239]
	v_exp_f32_e32 v232, v232
	v_exp_f32_e32 v233, v233
	v_exp_f32_e32 v234, v234
	v_exp_f32_e32 v235, v235
	v_pk_add_f32 v[232:233], v[232:233], 1.0 op_sel_hi:[1,0]
	v_pk_add_f32 v[234:235], v[234:235], 1.0 op_sel_hi:[1,0]
	v_rcp_f32_e32 v232, v232
	v_rcp_f32_e32 v233, v233
	v_rcp_f32_e32 v234, v234
	v_rcp_f32_e32 v235, v235
	v_pk_mul_f32 v[224:225], v[224:225], v[232:233]
	v_pk_mul_f32 v[226:227], v[226:227], v[234:235]
	v_pk_mul_f32 v[224:225], v[224:225], v[228:229]
	v_pk_mul_f32 v[226:227], v[226:227], v[230:231]
	v_cvt_pk_bf16_f32 v236, v224, v225
	v_cvt_pk_bf16_f32 v237, v226, v227
	v_add_u32_e32 v213, 0xb0000, v210
	global_store_dwordx2 v213, v[236:237], s[36:37] offset:8
	v_pk_fma_f32 v[224:225], v[180:181], v[20:21], v[188:189]
	v_pk_fma_f32 v[226:227], v[182:183], v[22:23], v[190:191]
	v_fmac_f32_dpp v224, v20, v176 row_shr:1 row_mask:0xf bank_mask:0xf
	v_fmac_f32_dpp v225, v21, v177 row_shr:1 row_mask:0xf bank_mask:0xf
	v_fmac_f32_dpp v226, v22, v178 row_shr:1 row_mask:0xf bank_mask:0xf
	v_fmac_f32_dpp v227, v23, v179 row_shr:1 row_mask:0xf bank_mask:0xf
	v_fmac_f32_dpp v224, v28, v176 row_shl:15 row_mask:0xf bank_mask:0xf
	v_fmac_f32_dpp v225, v29, v177 row_shl:15 row_mask:0xf bank_mask:0xf
	v_fmac_f32_dpp v226, v30, v178 row_shl:15 row_mask:0xf bank_mask:0xf
	v_fmac_f32_dpp v227, v31, v179 row_shl:15 row_mask:0xf bank_mask:0xf
	v_fmac_f32_dpp v224, v20, v184 row_shl:1 row_mask:0xf bank_mask:0xf
	v_fmac_f32_dpp v225, v21, v185 row_shl:1 row_mask:0xf bank_mask:0xf
	v_fmac_f32_dpp v226, v22, v186 row_shl:1 row_mask:0xf bank_mask:0xf
	v_fmac_f32_dpp v227, v23, v187 row_shl:1 row_mask:0xf bank_mask:0xf
	v_fmac_f32_dpp v224, v12, v184 row_shr:15 row_mask:0xf bank_mask:0xf
	v_fmac_f32_dpp v225, v13, v185 row_shr:15 row_mask:0xf bank_mask:0xf
	v_fmac_f32_dpp v226, v14, v186 row_shr:15 row_mask:0xf bank_mask:0xf
	v_fmac_f32_dpp v227, v15, v187 row_shr:15 row_mask:0xf bank_mask:0xf
	v_pk_fma_f32 v[228:229], v[196:197], v[16:17], v[204:205]
	v_pk_fma_f32 v[230:231], v[198:199], v[18:19], v[206:207]
	v_fmac_f32_dpp v228, v16, v192 row_shr:1 row_mask:0xf bank_mask:0xf
	v_fmac_f32_dpp v229, v17, v193 row_shr:1 row_mask:0xf bank_mask:0xf
	v_fmac_f32_dpp v230, v18, v194 row_shr:1 row_mask:0xf bank_mask:0xf
	v_fmac_f32_dpp v231, v19, v195 row_shr:1 row_mask:0xf bank_mask:0xf
	v_fmac_f32_dpp v228, v24, v192 row_shl:15 row_mask:0xf bank_mask:0xf
	v_fmac_f32_dpp v229, v25, v193 row_shl:15 row_mask:0xf bank_mask:0xf
	v_fmac_f32_dpp v230, v26, v194 row_shl:15 row_mask:0xf bank_mask:0xf
	v_fmac_f32_dpp v231, v27, v195 row_shl:15 row_mask:0xf bank_mask:0xf
	v_fmac_f32_dpp v228, v16, v200 row_shl:1 row_mask:0xf bank_mask:0xf
	v_fmac_f32_dpp v229, v17, v201 row_shl:1 row_mask:0xf bank_mask:0xf
	v_fmac_f32_dpp v230, v18, v202 row_shl:1 row_mask:0xf bank_mask:0xf
	v_fmac_f32_dpp v231, v19, v203 row_shl:1 row_mask:0xf bank_mask:0xf
	v_fmac_f32_dpp v228, v8, v200 row_shr:15 row_mask:0xf bank_mask:0xf
	v_fmac_f32_dpp v229, v9, v201 row_shr:15 row_mask:0xf bank_mask:0xf
	v_fmac_f32_dpp v230, v10, v202 row_shr:15 row_mask:0xf bank_mask:0xf
	v_fmac_f32_dpp v231, v11, v203 row_shr:15 row_mask:0xf bank_mask:0xf
	v_pk_mul_f32 v[232:233], v[224:225], v[238:239]
	v_pk_mul_f32 v[234:235], v[226:227], v[238:239]
	v_exp_f32_e32 v232, v232
	v_exp_f32_e32 v233, v233
	v_exp_f32_e32 v234, v234
	v_exp_f32_e32 v235, v235
	v_pk_add_f32 v[232:233], v[232:233], 1.0 op_sel_hi:[1,0]
	v_pk_add_f32 v[234:235], v[234:235], 1.0 op_sel_hi:[1,0]
	v_rcp_f32_e32 v232, v232
	v_rcp_f32_e32 v233, v233
	v_rcp_f32_e32 v234, v234
	v_rcp_f32_e32 v235, v235
	v_pk_mul_f32 v[224:225], v[224:225], v[232:233]
	v_pk_mul_f32 v[226:227], v[226:227], v[234:235]
	v_pk_mul_f32 v[224:225], v[224:225], v[228:229]
	v_pk_mul_f32 v[226:227], v[226:227], v[230:231]
	v_cvt_pk_bf16_f32 v236, v224, v225
	v_cvt_pk_bf16_f32 v237, v226, v227
	v_add_u32_e32 v213, 0xc6000, v210
	global_store_dwordx2 v213, v[236:237], s[36:37] offset:8
	v_pk_fma_f32 v[224:225], v[180:181], v[12:13], v[188:189]
	v_pk_fma_f32 v[226:227], v[182:183], v[14:15], v[190:191]
	v_fmac_f32_dpp v224, v12, v176 row_shr:1 row_mask:0xf bank_mask:0xf
	v_fmac_f32_dpp v225, v13, v177 row_shr:1 row_mask:0xf bank_mask:0xf
	v_fmac_f32_dpp v226, v14, v178 row_shr:1 row_mask:0xf bank_mask:0xf
	v_fmac_f32_dpp v227, v15, v179 row_shr:1 row_mask:0xf bank_mask:0xf
	v_fmac_f32_dpp v224, v20, v176 row_shl:15 row_mask:0xf bank_mask:0xf
	v_fmac_f32_dpp v225, v21, v177 row_shl:15 row_mask:0xf bank_mask:0xf
	v_fmac_f32_dpp v226, v22, v178 row_shl:15 row_mask:0xf bank_mask:0xf
	v_fmac_f32_dpp v227, v23, v179 row_shl:15 row_mask:0xf bank_mask:0xf
	v_fmac_f32_dpp v224, v12, v184 row_shl:1 row_mask:0xf bank_mask:0xf
	v_fmac_f32_dpp v225, v13, v185 row_shl:1 row_mask:0xf bank_mask:0xf
	v_fmac_f32_dpp v226, v14, v186 row_shl:1 row_mask:0xf bank_mask:0xf
	v_fmac_f32_dpp v227, v15, v187 row_shl:1 row_mask:0xf bank_mask:0xf
	v_fmac_f32_dpp v224, v4, v184 row_shr:15 row_mask:0xf bank_mask:0xf
	v_fmac_f32_dpp v225, v5, v185 row_shr:15 row_mask:0xf bank_mask:0xf
	v_fmac_f32_dpp v226, v6, v186 row_shr:15 row_mask:0xf bank_mask:0xf
	v_fmac_f32_dpp v227, v7, v187 row_shr:15 row_mask:0xf bank_mask:0xf
	v_pk_fma_f32 v[228:229], v[196:197], v[8:9], v[204:205]
	v_pk_fma_f32 v[230:231], v[198:199], v[10:11], v[206:207]
	v_fmac_f32_dpp v228, v8, v192 row_shr:1 row_mask:0xf bank_mask:0xf
	v_fmac_f32_dpp v229, v9, v193 row_shr:1 row_mask:0xf bank_mask:0xf
	v_fmac_f32_dpp v230, v10, v194 row_shr:1 row_mask:0xf bank_mask:0xf
	v_fmac_f32_dpp v231, v11, v195 row_shr:1 row_mask:0xf bank_mask:0xf
	v_fmac_f32_dpp v228, v16, v192 row_shl:15 row_mask:0xf bank_mask:0xf
	v_fmac_f32_dpp v229, v17, v193 row_shl:15 row_mask:0xf bank_mask:0xf
	v_fmac_f32_dpp v230, v18, v194 row_shl:15 row_mask:0xf bank_mask:0xf
	v_fmac_f32_dpp v231, v19, v195 row_shl:15 row_mask:0xf bank_mask:0xf
	v_fmac_f32_dpp v228, v8, v200 row_shl:1 row_mask:0xf bank_mask:0xf
	v_fmac_f32_dpp v229, v9, v201 row_shl:1 row_mask:0xf bank_mask:0xf
	v_fmac_f32_dpp v230, v10, v202 row_shl:1 row_mask:0xf bank_mask:0xf
	v_fmac_f32_dpp v231, v11, v203 row_shl:1 row_mask:0xf bank_mask:0xf
	v_fmac_f32_dpp v228, v0, v200 row_shr:15 row_mask:0xf bank_mask:0xf
	v_fmac_f32_dpp v229, v1, v201 row_shr:15 row_mask:0xf bank_mask:0xf
	v_fmac_f32_dpp v230, v2, v202 row_shr:15 row_mask:0xf bank_mask:0xf
	v_fmac_f32_dpp v231, v3, v203 row_shr:15 row_mask:0xf bank_mask:0xf
	v_pk_mul_f32 v[232:233], v[224:225], v[238:239]
	v_pk_mul_f32 v[234:235], v[226:227], v[238:239]
	v_exp_f32_e32 v232, v232
	v_exp_f32_e32 v233, v233
	v_exp_f32_e32 v234, v234
	v_exp_f32_e32 v235, v235
	v_pk_add_f32 v[232:233], v[232:233], 1.0 op_sel_hi:[1,0]
	v_pk_add_f32 v[234:235], v[234:235], 1.0 op_sel_hi:[1,0]
	v_rcp_f32_e32 v232, v232
	v_rcp_f32_e32 v233, v233
	v_rcp_f32_e32 v234, v234
	v_rcp_f32_e32 v235, v235
	v_pk_mul_f32 v[224:225], v[224:225], v[232:233]
	v_pk_mul_f32 v[226:227], v[226:227], v[234:235]
	v_pk_mul_f32 v[224:225], v[224:225], v[228:229]
	v_pk_mul_f32 v[226:227], v[226:227], v[230:231]
	v_cvt_pk_bf16_f32 v236, v224, v225
	v_cvt_pk_bf16_f32 v237, v226, v227
	v_add_u32_e32 v213, 0xdc000, v210
	global_store_dwordx2 v213, v[236:237], s[36:37] offset:8
	v_pk_fma_f32 v[224:225], v[180:181], v[4:5], v[188:189]
	v_pk_fma_f32 v[226:227], v[182:183], v[6:7], v[190:191]
	v_fmac_f32_dpp v224, v4, v176 row_shr:1 row_mask:0xf bank_mask:0xf
	v_fmac_f32_dpp v225, v5, v177 row_shr:1 row_mask:0xf bank_mask:0xf
	v_fmac_f32_dpp v226, v6, v178 row_shr:1 row_mask:0xf bank_mask:0xf
	v_fmac_f32_dpp v227, v7, v179 row_shr:1 row_mask:0xf bank_mask:0xf
	v_fmac_f32_dpp v224, v12, v176 row_shl:15 row_mask:0xf bank_mask:0xf
	v_fmac_f32_dpp v225, v13, v177 row_shl:15 row_mask:0xf bank_mask:0xf
	v_fmac_f32_dpp v226, v14, v178 row_shl:15 row_mask:0xf bank_mask:0xf
	v_fmac_f32_dpp v227, v15, v179 row_shl:15 row_mask:0xf bank_mask:0xf
	v_fmac_f32_dpp v224, v4, v184 row_shl:1 row_mask:0xf bank_mask:0xf
	v_fmac_f32_dpp v225, v5, v185 row_shl:1 row_mask:0xf bank_mask:0xf
	v_fmac_f32_dpp v226, v6, v186 row_shl:1 row_mask:0xf bank_mask:0xf
	v_fmac_f32_dpp v227, v7, v187 row_shl:1 row_mask:0xf bank_mask:0xf
	v_pk_fma_f32 v[228:229], v[196:197], v[0:1], v[204:205]
	v_pk_fma_f32 v[230:231], v[198:199], v[2:3], v[206:207]
	v_fmac_f32_dpp v228, v0, v192 row_shr:1 row_mask:0xf bank_mask:0xf
	v_fmac_f32_dpp v229, v1, v193 row_shr:1 row_mask:0xf bank_mask:0xf
	v_fmac_f32_dpp v230, v2, v194 row_shr:1 row_mask:0xf bank_mask:0xf
	v_fmac_f32_dpp v231, v3, v195 row_shr:1 row_mask:0xf bank_mask:0xf
	v_fmac_f32_dpp v228, v8, v192 row_shl:15 row_mask:0xf bank_mask:0xf
	v_fmac_f32_dpp v229, v9, v193 row_shl:15 row_mask:0xf bank_mask:0xf
	v_fmac_f32_dpp v230, v10, v194 row_shl:15 row_mask:0xf bank_mask:0xf
	v_fmac_f32_dpp v231, v11, v195 row_shl:15 row_mask:0xf bank_mask:0xf
	v_fmac_f32_dpp v228, v0, v200 row_shl:1 row_mask:0xf bank_mask:0xf
	v_fmac_f32_dpp v229, v1, v201 row_shl:1 row_mask:0xf bank_mask:0xf
	v_fmac_f32_dpp v230, v2, v202 row_shl:1 row_mask:0xf bank_mask:0xf
	v_fmac_f32_dpp v231, v3, v203 row_shl:1 row_mask:0xf bank_mask:0xf
	v_pk_mul_f32 v[232:233], v[224:225], v[238:239]
	v_pk_mul_f32 v[234:235], v[226:227], v[238:239]
	v_exp_f32_e32 v232, v232
	v_exp_f32_e32 v233, v233
	v_exp_f32_e32 v234, v234
	v_exp_f32_e32 v235, v235
	v_pk_add_f32 v[232:233], v[232:233], 1.0 op_sel_hi:[1,0]
	v_pk_add_f32 v[234:235], v[234:235], 1.0 op_sel_hi:[1,0]
	v_rcp_f32_e32 v232, v232
	v_rcp_f32_e32 v233, v233
	v_rcp_f32_e32 v234, v234
	v_rcp_f32_e32 v235, v235
	v_pk_mul_f32 v[224:225], v[224:225], v[232:233]
	v_pk_mul_f32 v[226:227], v[226:227], v[234:235]
	v_pk_mul_f32 v[224:225], v[224:225], v[228:229]
	v_pk_mul_f32 v[226:227], v[226:227], v[230:231]
	v_cvt_pk_bf16_f32 v236, v224, v225
	v_cvt_pk_bf16_f32 v237, v226, v227
	v_add_u32_e32 v213, 0xf2000, v210
	global_store_dwordx2 v213, v[236:237], s[36:37] offset:8
	s_andn2_b64 vcc, exec, s[10:11]
	s_mov_b64 s[2:3], -1
	s_cbranch_vccnz .LBB0_1180
	s_andn2_b64 vcc, exec, s[96:97]
	s_cbranch_vccnz .LBB0_1179
	s_barrier
	s_branch .LBB0_1179
